# P7: epilogue bias (cb) loads hoisted to the unit's first K iteration into v[240:255]; no vmcnt(0) round trip at the epilogue start
# baseline (speedup 1.0000x reference)
;     __device__ __forceinline__ bool next(int i, Unit& u) const { if (!base.next(i >> 1, u)) return false; if (i & 1) { u.pm += 64; u.pn += 8; } return true; }
; #define PG8_STAGE(bufoff, gbase, voff) do { _Pragma("unroll") for (int _i = 0; _i < 2; ++_i) \
;         __builtin_amdgcn_global_load_lds((const unsigned*)((const char*)(gbase) + (voff)[_i]), (PG8_LAS unsigned*)(lds + (bufoff) + ldsw + _i * 8192), 16, 0, 0); } while (0)
; #define PG8_LDA(dst, b, h) do { _Pragma("unroll") for (int m = 0; m < 4; ++m) _Pragma("unroll") for (int k = 0; k < 2; ++k) dst[m][k] = *(const PG8_LAS bf16x8*)(lds + PG8_SA(b, h) + aoff + m * 2048 + k * 1024); } while (0)
;     __device__ __forceinline__ void operator()(const f32x4 (&acc)[2][2][4][2], const Unit& u, int wr, int wc, int fr, int fq) const {
;     ...
;         f32x4 cbv[2][2];
; #pragma unroll
;         for (int bj = 0; bj < 2; ++bj)
; #pragma unroll
;             for (int n = 0; n < 2; ++n) cbv[bj][n] = *(const f32x4*)(cb + (size_t)b * 8192 + col0 + bj * HALF + 4 * n);
; template <class Epi, class Sched, bool ALIGN_EPI = false, bool SP2 = false>
; __device__ __forceinline__ void gemm_phase(PG8_LAS unsigned char* lds, const Gemm g, const Sched& S, const Epi& E) {
;     ...
;         const bool has_next = S.next(ui + 1, nxt);
;         const char* nA = has_next ? (const char*)g.A + (size_t)nxt.pm * tstep : cA; const char* nB = has_next ? (const char*)g.Bt + (size_t)nxt.pn * tstep : cB;
;         for (int t = 0; t < nt; t += 2) {
;             const bool last = (t == nt - 2);
;             const char* a1 = cA + (size_t)(t + 1) * kstep;
;             const char* a2 = last ? nA : cA + (size_t)(t + 2) * kstep; const char* b2 = last ? nB : cB + (size_t)(t + 2) * kstep;
;             const char* a3 = a2 + kstep; const char* b3 = b2 + kstep;
;             if (last && has_next) S.a_ready(nxt);
;             if constexpr (SP2) {
;             PG8_LDB(B0, 0, 0); PG8_LDB(B1, 0, 1); PG8_SCHED; PG8_LDA(At, 0, 0); PG8_STAGE(PG8_SA(1, 1), a1 + hstep, voffA);
;             PG8_WAIT_V(8); PG8_WAIT_L(0); PG8_BAR; PG8_MMA(0, 0, At, B0); PG8_MMA(0, 1, At, B1); PG8_BAR; PG8_SCHED;
;             PG8_LDA(At, 0, 1); PG8_STAGE(PG8_SB(0, 0), b2, voffB); PG8_STAGE(PG8_SB(0, 1), b2 + hstep, voffB); PG8_STAGE(PG8_SA(0, 0), a2, voffA);
;             PG8_WAIT_V(8); PG8_WAIT_L(0); PG8_BAR; PG8_MMA(1, 0, At, B0); PG8_MMA(1, 1, At, B1); PG8_BAR; PG8_SCHED;
.LBB0_993:
	s_ashr_i32 s15, s14, 31
	s_lshl_b64 s[18:19], s[14:15], 20
	s_add_u32 s18, s8, s18
	s_addc_u32 s19, s9, s19
	s_and_b64 s[20:21], s[4:5], exec
	s_cselect_b32 s15, s19, s25
	s_cselect_b32 s43, s18, s24
	s_ashr_i32 s17, s16, 31
	s_lshl_b64 s[20:21], s[16:17], 20
	v_readlane_b32 s28, v236, 52
	v_readlane_b32 s29, v236, 53
	s_add_u32 s20, s28, s20
	s_addc_u32 s21, s29, s21
	s_and_b64 s[28:29], s[4:5], exec
	s_cselect_b32 s17, s21, s27
	s_cselect_b32 s44, s20, s26
	s_add_u32 s24, s24, 0x80080
	s_addc_u32 s25, s25, 0
	s_add_u32 s45, s26, 0x100
	s_addc_u32 s46, s27, 0
	s_mov_b32 s47, -2
	s_ashr_i32 s98, s22, 4
	s_ashr_i32 s99, s98, 31
	s_lshl_b64 s[98:99], s[98:99], 15
	s_add_u32 s98, s36, s98
	s_addc_u32 s99, s37, s99
	v_lshl_or_b32 v239, s42, 8, v171
	v_lshlrev_b32_e32 v239, 2, v239
	global_load_dwordx4 v[240:243], v239, s[98:99]
	global_load_dwordx4 v[244:247], v239, s[98:99] offset:16
	global_load_dwordx4 v[248:251], v239, s[98:99] offset:512
	global_load_dwordx4 v[252:255], v239, s[98:99] offset:528
	ds_read_b128 v[128:131], v173
	ds_read_b128 v[132:135], v173 offset:1024
	ds_read_b128 v[136:139], v173 offset:2048
	ds_read_b128 v[140:143], v173 offset:3072
	ds_read_b128 v[176:179], v174
	ds_read_b128 v[180:183], v174 offset:1024
	ds_read_b128 v[188:191], v174 offset:2048
	ds_read_b128 v[192:195], v174 offset:3072
	s_add_u32 s26, s24, 0xfff80080
	s_addc_u32 s27, s25, -1
	s_cmp_eq_u32 s47, 28
	s_cselect_b32 s29, s15, s27
	s_cselect_b32 s28, s43, s26
	s_cselect_b32 s27, s17, s46
	s_cselect_b32 s26, s44, s45
	v_lshl_add_u64 v[160:161], s[24:25], 0, v[152:153]
	s_add_i32 m0, s23, 0xc000
	ds_read_b128 v[196:199], v175
	ds_read_b128 v[200:203], v175 offset:1024
	ds_read_b128 v[204:207], v175 offset:2048
	ds_read_b128 v[208:211], v175 offset:3072
	ds_read_b128 v[212:215], v175 offset:4096
	ds_read_b128 v[216:219], v175 offset:5120
	ds_read_b128 v[220:223], v175 offset:6144
	ds_read_b128 v[224:227], v175 offset:7168
	global_load_lds_dwordx4 v[160:161], off
	v_lshl_add_u64 v[160:161], s[24:25], 0, v[154:155]
	s_add_i32 m0, s23, 0xe000
	s_nop 0
	global_load_lds_dwordx4 v[160:161], off
	s_setprio 1
	s_waitcnt vmcnt(12)
	s_waitcnt lgkmcnt(0)
	s_barrier
	v_mfma_f32_16x16x32_bf16 v[124:127], v[128:131], v[196:199], 0
	v_mfma_f32_16x16x32_bf16 v[120:123], v[136:139], v[196:199], 0
	v_mfma_f32_16x16x32_bf16 v[108:111], v[128:131], v[204:207], 0
	v_mfma_f32_16x16x32_bf16 v[104:107], v[136:139], v[204:207], 0
	v_mfma_f32_16x16x32_bf16 v[92:95], v[128:131], v[212:215], 0
	v_mfma_f32_16x16x32_bf16 v[88:91], v[136:139], v[212:215], 0
	v_mfma_f32_16x16x32_bf16 v[76:79], v[128:131], v[220:223], 0
	v_mfma_f32_16x16x32_bf16 v[72:75], v[136:139], v[220:223], 0
	v_mfma_f32_16x16x32_bf16 v[124:127], v[132:135], v[200:203], v[124:127]
	v_mfma_f32_16x16x32_bf16 v[120:123], v[140:143], v[200:203], v[120:123]
	v_mfma_f32_16x16x32_bf16 v[108:111], v[132:135], v[208:211], v[108:111]
	v_mfma_f32_16x16x32_bf16 v[104:107], v[140:143], v[208:211], v[104:107]
	v_mfma_f32_16x16x32_bf16 v[92:95], v[132:135], v[216:219], v[92:95]
	v_mfma_f32_16x16x32_bf16 v[88:91], v[140:143], v[216:219], v[88:91]
	v_mfma_f32_16x16x32_bf16 v[76:79], v[132:135], v[224:227], v[76:79]
	v_mfma_f32_16x16x32_bf16 v[72:75], v[140:143], v[224:227], v[72:75]
	s_setprio 0
	s_setprio 1
	v_mfma_f32_16x16x32_bf16 v[116:119], v[176:179], v[196:199], 0
	v_mfma_f32_16x16x32_bf16 v[112:115], v[188:191], v[196:199], 0
	v_mfma_f32_16x16x32_bf16 v[100:103], v[176:179], v[204:207], 0
	v_mfma_f32_16x16x32_bf16 v[96:99], v[188:191], v[204:207], 0
	v_mfma_f32_16x16x32_bf16 v[84:87], v[176:179], v[212:215], 0
	v_mfma_f32_16x16x32_bf16 v[80:83], v[188:191], v[212:215], 0
	v_mfma_f32_16x16x32_bf16 v[68:71], v[176:179], v[220:223], 0
	v_mfma_f32_16x16x32_bf16 v[64:67], v[188:191], v[220:223], 0
	v_mfma_f32_16x16x32_bf16 v[116:119], v[180:183], v[200:203], v[116:119]
	v_mfma_f32_16x16x32_bf16 v[112:115], v[192:195], v[200:203], v[112:115]
	v_mfma_f32_16x16x32_bf16 v[100:103], v[180:183], v[208:211], v[100:103]
	v_mfma_f32_16x16x32_bf16 v[96:99], v[192:195], v[208:211], v[96:99]
	v_mfma_f32_16x16x32_bf16 v[84:87], v[180:183], v[216:219], v[84:87]
	v_mfma_f32_16x16x32_bf16 v[80:83], v[192:195], v[216:219], v[80:83]
	v_mfma_f32_16x16x32_bf16 v[68:71], v[180:183], v[224:227], v[68:71]
	v_mfma_f32_16x16x32_bf16 v[64:67], v[192:195], v[224:227], v[64:67]
	s_barrier
	s_setprio 0
	s_add_i32 s48, s40, s31
	v_lshl_add_u64 v[160:161], s[26:27], 0, v[146:147]
	s_mov_b32 m0, s48
	ds_read_b128 v[196:199], v175 offset:16384
	ds_read_b128 v[200:203], v175 offset:17408
	ds_read_b128 v[204:207], v175 offset:18432
	ds_read_b128 v[208:211], v175 offset:19456
	ds_read_b128 v[212:215], v175 offset:20480
	ds_read_b128 v[216:219], v175 offset:21504
	ds_read_b128 v[220:223], v175 offset:22528
	ds_read_b128 v[224:227], v175 offset:23552
	global_load_lds_dwordx4 v[160:161], off
	s_add_i32 m0, s48, 0x2000
	s_add_u32 s48, s26, 0x80000
	v_lshl_add_u64 v[184:185], s[26:27], 0, v[150:151]
	s_addc_u32 s49, s27, 0
	s_add_i32 s50, s41, s31
	global_load_lds_dwordx4 v[184:185], off
	v_lshl_add_u64 v[228:229], s[48:49], 0, v[146:147]
	s_mov_b32 m0, s50
	v_lshl_add_u64 v[230:231], s[28:29], 0, v[148:149]
	global_load_lds_dwordx4 v[228:229], off
	v_lshl_add_u64 v[228:229], s[48:49], 0, v[150:151]
	s_add_i32 m0, s50, 0x2000
	s_nop 0
	global_load_lds_dwordx4 v[228:229], off
	v_lshl_add_u64 v[228:229], s[28:29], 0, v[144:145]
	s_mov_b32 m0, s23
	s_nop 0
	global_load_lds_dwordx4 v[228:229], off
	s_mov_b32 m0, s33
	s_nop 0
	global_load_lds_dwordx4 v[230:231], off
	s_setprio 1
	s_waitcnt vmcnt(12)
	s_waitcnt lgkmcnt(0)
	s_barrier
; #define PG8_STAGE(bufoff, gbase, voff) do { _Pragma("unroll") for (int _i = 0; _i < 2; ++_i) \
;         __builtin_amdgcn_global_load_lds((const unsigned*)((const char*)(gbase) + (voff)[_i]), (PG8_LAS unsigned*)(lds + (bufoff) + ldsw + _i * 8192), 16, 0, 0); } while (0)
; #define PG8_LDA(dst, b, h) do { _Pragma("unroll") for (int m = 0; m < 4; ++m) _Pragma("unroll") for (int k = 0; k < 2; ++k) dst[m][k] = *(const PG8_LAS bf16x8*)(lds + PG8_SA(b, h) + aoff + m * 2048 + k * 1024); } while (0)
; #define PG8_LDB(dst, b, h) do { _Pragma("unroll") for (int n = 0; n < 2; ++n) _Pragma("unroll") for (int k = 0; k < 2; ++k) dst[n][k] = *(const PG8_LAS bf16x8*)(lds + PG8_SB(b, h) + boff + n * 2048 + k * 1024); } while (0)
; #define PG8_MMA(ai, bj, At, Bt) do { __builtin_amdgcn_s_setprio(1); _Pragma("unroll") for (int m = 0; m < 4; ++m) _Pragma("unroll") for (int n = 0; n < 2; ++n) _Pragma("unroll") for (int k = 0; k < 2; ++k) \
;         acc[ai][bj][m][n] = __builtin_amdgcn_mfma_f32_16x16x32_bf16(Bt[n][k], At[m][k], acc[ai][bj][m][n], 0, 0, 0); __builtin_amdgcn_s_setprio(0); } while (0)
; #define PG8_WAIT_V(n) asm volatile("s_waitcnt vmcnt(" #n ")" ::: "memory")
; #define PG8_WAIT_L(n) asm volatile("s_waitcnt lgkmcnt(" #n ")" ::: "memory")
; #define PG8_BAR __builtin_amdgcn_s_barrier()
; #define PG8_SCHED __builtin_amdgcn_sched_barrier(0)
; template <class Epi, class Sched, bool ALIGN_EPI = false, bool SP2 = false>
; __device__ __forceinline__ void gemm_phase(PG8_LAS unsigned char* lds, const Gemm g, const Sched& S, const Epi& E) {
;     ...
;             PG8_WAIT_V(8); PG8_WAIT_L(0); PG8_BAR; PG8_MMA(1, 0, At, B0); PG8_MMA(1, 1, At, B1); PG8_BAR; PG8_SCHED;
;             PG8_LDB(B0, 1, 0); PG8_LDB(B1, 1, 1); PG8_SCHED; PG8_LDA(At, 1, 0); PG8_STAGE(PG8_SA(0, 1), a2 + hstep, voffA);
;             PG8_WAIT_V(8); PG8_WAIT_L(0); PG8_BAR; PG8_MMA(0, 0, At, B0); PG8_MMA(0, 1, At, B1); PG8_BAR; PG8_SCHED;
	v_mfma_f32_16x16x32_bf16 v[60:63], v[128:131], v[196:199], 0
	v_mfma_f32_16x16x32_bf16 v[56:59], v[136:139], v[196:199], 0
	v_mfma_f32_16x16x32_bf16 v[44:47], v[128:131], v[204:207], 0
	v_mfma_f32_16x16x32_bf16 v[40:43], v[136:139], v[204:207], 0
	v_mfma_f32_16x16x32_bf16 v[28:31], v[128:131], v[212:215], 0
	v_mfma_f32_16x16x32_bf16 v[24:27], v[136:139], v[212:215], 0
	v_mfma_f32_16x16x32_bf16 v[12:15], v[128:131], v[220:223], 0
	v_mfma_f32_16x16x32_bf16 v[8:11], v[136:139], v[220:223], 0
	v_mfma_f32_16x16x32_bf16 v[60:63], v[132:135], v[200:203], v[60:63]
	v_mfma_f32_16x16x32_bf16 v[56:59], v[140:143], v[200:203], v[56:59]
	v_mfma_f32_16x16x32_bf16 v[44:47], v[132:135], v[208:211], v[44:47]
	v_mfma_f32_16x16x32_bf16 v[40:43], v[140:143], v[208:211], v[40:43]
	v_mfma_f32_16x16x32_bf16 v[28:31], v[132:135], v[216:219], v[28:31]
	v_mfma_f32_16x16x32_bf16 v[24:27], v[140:143], v[216:219], v[24:27]
	v_mfma_f32_16x16x32_bf16 v[12:15], v[132:135], v[224:227], v[12:15]
	v_mfma_f32_16x16x32_bf16 v[8:11], v[140:143], v[224:227], v[8:11]
	s_setprio 0
	s_setprio 1
	v_mfma_f32_16x16x32_bf16 v[52:55], v[176:179], v[196:199], 0
	v_mfma_f32_16x16x32_bf16 v[48:51], v[188:191], v[196:199], 0
	v_mfma_f32_16x16x32_bf16 v[36:39], v[176:179], v[204:207], 0
	v_mfma_f32_16x16x32_bf16 v[32:35], v[188:191], v[204:207], 0
	v_mfma_f32_16x16x32_bf16 v[20:23], v[176:179], v[212:215], 0
	v_mfma_f32_16x16x32_bf16 v[16:19], v[188:191], v[212:215], 0
	v_mfma_f32_16x16x32_bf16 v[4:7], v[176:179], v[220:223], 0
	v_mfma_f32_16x16x32_bf16 v[0:3], v[188:191], v[220:223], 0
	v_mfma_f32_16x16x32_bf16 v[52:55], v[180:183], v[200:203], v[52:55]
	v_mfma_f32_16x16x32_bf16 v[48:51], v[192:195], v[200:203], v[48:51]
	v_mfma_f32_16x16x32_bf16 v[36:39], v[180:183], v[208:211], v[36:39]
	v_mfma_f32_16x16x32_bf16 v[32:35], v[192:195], v[208:211], v[32:35]
	v_mfma_f32_16x16x32_bf16 v[20:23], v[180:183], v[216:219], v[20:23]
	v_mfma_f32_16x16x32_bf16 v[16:19], v[192:195], v[216:219], v[16:19]
	v_mfma_f32_16x16x32_bf16 v[4:7], v[180:183], v[224:227], v[4:7]
	v_mfma_f32_16x16x32_bf16 v[0:3], v[192:195], v[224:227], v[0:3]
	s_barrier
	s_setprio 0
	s_add_i32 s48, 0, 0x18000
	s_add_i32 s49, 0, 0x1c000
	v_add_u32_e32 v140, s48, v163
	v_add_u32_e32 v187, s49, v163
	ds_read_b128 v[128:131], v140
	ds_read_b128 v[132:135], v140 offset:1024
	ds_read_b128 v[136:139], v140 offset:2048
	ds_read_b128 v[140:143], v140 offset:3072
	ds_read_b128 v[176:179], v187
	ds_read_b128 v[180:183], v187 offset:1024
	ds_read_b128 v[188:191], v187 offset:2048
	ds_read_b128 v[192:195], v187 offset:3072
	s_add_u32 s28, s28, 0x80000
	s_addc_u32 s29, s29, 0
	s_mov_b32 m0, s34
	v_lshl_add_u64 v[232:233], s[28:29], 0, v[144:145]
	ds_read_b128 v[196:199], v175 offset:32768
	ds_read_b128 v[200:203], v175 offset:33792
	ds_read_b128 v[204:207], v175 offset:34816
	ds_read_b128 v[208:211], v175 offset:35840
	ds_read_b128 v[212:215], v175 offset:36864
	ds_read_b128 v[216:219], v175 offset:37888
	ds_read_b128 v[220:223], v175 offset:38912
	ds_read_b128 v[224:227], v175 offset:39936
	global_load_lds_dwordx4 v[232:233], off
	v_lshl_add_u64 v[232:233], s[28:29], 0, v[148:149]
	s_mov_b32 m0, s35
	s_nop 0
	global_load_lds_dwordx4 v[232:233], off
	s_setprio 1
	s_waitcnt vmcnt(8)
	s_waitcnt lgkmcnt(0)
	s_barrier
	v_mfma_f32_16x16x32_bf16 v[124:127], v[128:131], v[196:199], v[124:127]
	v_mfma_f32_16x16x32_bf16 v[120:123], v[136:139], v[196:199], v[120:123]
	v_mfma_f32_16x16x32_bf16 v[108:111], v[128:131], v[204:207], v[108:111]
	v_mfma_f32_16x16x32_bf16 v[104:107], v[136:139], v[204:207], v[104:107]
	v_mfma_f32_16x16x32_bf16 v[92:95], v[128:131], v[212:215], v[92:95]
	v_mfma_f32_16x16x32_bf16 v[88:91], v[136:139], v[212:215], v[88:91]
	v_mfma_f32_16x16x32_bf16 v[76:79], v[128:131], v[220:223], v[76:79]
	v_mfma_f32_16x16x32_bf16 v[72:75], v[136:139], v[220:223], v[72:75]
	v_mfma_f32_16x16x32_bf16 v[124:127], v[132:135], v[200:203], v[124:127]
	v_mfma_f32_16x16x32_bf16 v[120:123], v[140:143], v[200:203], v[120:123]
	v_mfma_f32_16x16x32_bf16 v[108:111], v[132:135], v[208:211], v[108:111]
	v_mfma_f32_16x16x32_bf16 v[104:107], v[140:143], v[208:211], v[104:107]
	v_mfma_f32_16x16x32_bf16 v[92:95], v[132:135], v[216:219], v[92:95]
	v_mfma_f32_16x16x32_bf16 v[88:91], v[140:143], v[216:219], v[88:91]
	v_mfma_f32_16x16x32_bf16 v[76:79], v[132:135], v[224:227], v[76:79]
	v_mfma_f32_16x16x32_bf16 v[72:75], v[140:143], v[224:227], v[72:75]
	s_setprio 0
	s_setprio 1
	v_mfma_f32_16x16x32_bf16 v[116:119], v[176:179], v[196:199], v[116:119]
	v_mfma_f32_16x16x32_bf16 v[112:115], v[188:191], v[196:199], v[112:115]
	v_mfma_f32_16x16x32_bf16 v[100:103], v[176:179], v[204:207], v[100:103]
	v_mfma_f32_16x16x32_bf16 v[96:99], v[188:191], v[204:207], v[96:99]
	v_mfma_f32_16x16x32_bf16 v[84:87], v[176:179], v[212:215], v[84:87]
	v_mfma_f32_16x16x32_bf16 v[80:83], v[188:191], v[212:215], v[80:83]
	v_mfma_f32_16x16x32_bf16 v[68:71], v[176:179], v[220:223], v[68:71]
	v_mfma_f32_16x16x32_bf16 v[64:67], v[188:191], v[220:223], v[64:67]
	v_mfma_f32_16x16x32_bf16 v[116:119], v[180:183], v[200:203], v[116:119]
	v_mfma_f32_16x16x32_bf16 v[112:115], v[192:195], v[200:203], v[112:115]
	v_mfma_f32_16x16x32_bf16 v[100:103], v[180:183], v[208:211], v[100:103]
	v_mfma_f32_16x16x32_bf16 v[96:99], v[192:195], v[208:211], v[96:99]
	v_mfma_f32_16x16x32_bf16 v[84:87], v[180:183], v[216:219], v[84:87]
	v_mfma_f32_16x16x32_bf16 v[80:83], v[192:195], v[216:219], v[80:83]
	v_mfma_f32_16x16x32_bf16 v[68:71], v[180:183], v[224:227], v[68:71]
	v_mfma_f32_16x16x32_bf16 v[64:67], v[192:195], v[224:227], v[64:67]
	s_barrier
; #define PG8_STAGE(bufoff, gbase, voff) do { _Pragma("unroll") for (int _i = 0; _i < 2; ++_i) \
;         __builtin_amdgcn_global_load_lds((const unsigned*)((const char*)(gbase) + (voff)[_i]), (PG8_LAS unsigned*)(lds + (bufoff) + ldsw + _i * 8192), 16, 0, 0); } while (0)
; #define PG8_LDA(dst, b, h) do { _Pragma("unroll") for (int m = 0; m < 4; ++m) _Pragma("unroll") for (int k = 0; k < 2; ++k) dst[m][k] = *(const PG8_LAS bf16x8*)(lds + PG8_SA(b, h) + aoff + m * 2048 + k * 1024); } while (0)
; #define PG8_MMA(ai, bj, At, Bt) do { __builtin_amdgcn_s_setprio(1); _Pragma("unroll") for (int m = 0; m < 4; ++m) _Pragma("unroll") for (int n = 0; n < 2; ++n) _Pragma("unroll") for (int k = 0; k < 2; ++k) \
;         acc[ai][bj][m][n] = __builtin_amdgcn_mfma_f32_16x16x32_bf16(Bt[n][k], At[m][k], acc[ai][bj][m][n], 0, 0, 0); __builtin_amdgcn_s_setprio(0); } while (0)
; #define PG8_WAIT_V(n) asm volatile("s_waitcnt vmcnt(" #n ")" ::: "memory")
; #define PG8_WAIT_L(n) asm volatile("s_waitcnt lgkmcnt(" #n ")" ::: "memory")
; #define PG8_BAR __builtin_amdgcn_s_barrier()
; #define PG8_SCHED __builtin_amdgcn_sched_barrier(0)
; template <class Epi, class Sched, bool ALIGN_EPI = false, bool SP2 = false>
; __device__ __forceinline__ void gemm_phase(PG8_LAS unsigned char* lds, const Gemm g, const Sched& S, const Epi& E) {
;     ...
;         for (int t = 0; t < nt; t += 2) {
;     ...
;             PG8_LDA(At, 1, 1); PG8_STAGE(PG8_SB(1, 0), b3, voffB); PG8_STAGE(PG8_SB(1, 1), b3 + hstep, voffB); PG8_STAGE(PG8_SA(1, 0), a3, voffA);
;             PG8_WAIT_V(8); PG8_WAIT_L(0); PG8_BAR; PG8_MMA(1, 0, At, B0); PG8_MMA(1, 1, At, B1); PG8_BAR; PG8_SCHED;
	s_setprio 0
	s_add_i32 s28, s48, s31
	v_lshl_add_u64 v[160:161], v[160:161], 0, s[10:11]
	s_mov_b32 m0, s28
	ds_read_b128 v[196:199], v175 offset:49152
	ds_read_b128 v[200:203], v175 offset:50176
	ds_read_b128 v[204:207], v175 offset:51200
	ds_read_b128 v[208:211], v175 offset:52224
	ds_read_b128 v[212:215], v175 offset:53248
	ds_read_b128 v[216:219], v175 offset:54272
	ds_read_b128 v[220:223], v175 offset:55296
	ds_read_b128 v[224:227], v175 offset:56320
	global_load_lds_dwordx4 v[160:161], off
	s_add_i32 m0, s28, 0x2000
	s_add_u32 s26, s26, 0x80080
	v_lshl_add_u64 v[160:161], v[184:185], 0, s[10:11]
	s_addc_u32 s27, s27, 0
	s_add_i32 s28, s49, s31
	global_load_lds_dwordx4 v[160:161], off
	v_lshl_add_u64 v[160:161], s[26:27], 0, v[146:147]
	s_mov_b32 m0, s28
	s_nop 0
	global_load_lds_dwordx4 v[160:161], off
	v_lshl_add_u64 v[160:161], s[26:27], 0, v[150:151]
	s_add_i32 m0, s28, 0x2000
	s_nop 0
	global_load_lds_dwordx4 v[160:161], off
	v_lshl_add_u64 v[160:161], v[228:229], 0, s[10:11]
	s_mov_b32 m0, s38
	s_nop 0
	global_load_lds_dwordx4 v[160:161], off
	v_lshl_add_u64 v[160:161], v[230:231], 0, s[10:11]
	s_mov_b32 m0, s39
	s_nop 0
	global_load_lds_dwordx4 v[160:161], off
	s_setprio 1
	s_waitcnt vmcnt(8)
	s_waitcnt lgkmcnt(0)
	s_barrier
	v_mfma_f32_16x16x32_bf16 v[60:63], v[128:131], v[196:199], v[60:63]
	v_mfma_f32_16x16x32_bf16 v[56:59], v[136:139], v[196:199], v[56:59]
	v_mfma_f32_16x16x32_bf16 v[44:47], v[128:131], v[204:207], v[44:47]
	v_mfma_f32_16x16x32_bf16 v[40:43], v[136:139], v[204:207], v[40:43]
	v_mfma_f32_16x16x32_bf16 v[28:31], v[128:131], v[212:215], v[28:31]
	v_mfma_f32_16x16x32_bf16 v[24:27], v[136:139], v[212:215], v[24:27]
	v_mfma_f32_16x16x32_bf16 v[12:15], v[128:131], v[220:223], v[12:15]
	v_mfma_f32_16x16x32_bf16 v[8:11], v[136:139], v[220:223], v[8:11]
	v_mfma_f32_16x16x32_bf16 v[60:63], v[132:135], v[200:203], v[60:63]
	v_mfma_f32_16x16x32_bf16 v[56:59], v[140:143], v[200:203], v[56:59]
	v_mfma_f32_16x16x32_bf16 v[44:47], v[132:135], v[208:211], v[44:47]
	v_mfma_f32_16x16x32_bf16 v[40:43], v[140:143], v[208:211], v[40:43]
	v_mfma_f32_16x16x32_bf16 v[28:31], v[132:135], v[216:219], v[28:31]
	v_mfma_f32_16x16x32_bf16 v[24:27], v[140:143], v[216:219], v[24:27]
	v_mfma_f32_16x16x32_bf16 v[12:15], v[132:135], v[224:227], v[12:15]
	v_mfma_f32_16x16x32_bf16 v[8:11], v[140:143], v[224:227], v[8:11]
	s_setprio 0
	s_setprio 1
	v_mfma_f32_16x16x32_bf16 v[52:55], v[176:179], v[196:199], v[52:55]
	v_mfma_f32_16x16x32_bf16 v[48:51], v[188:191], v[196:199], v[48:51]
	v_mfma_f32_16x16x32_bf16 v[36:39], v[176:179], v[204:207], v[36:39]
	v_mfma_f32_16x16x32_bf16 v[32:35], v[188:191], v[204:207], v[32:35]
	v_mfma_f32_16x16x32_bf16 v[20:23], v[176:179], v[212:215], v[20:23]
	v_mfma_f32_16x16x32_bf16 v[16:19], v[188:191], v[212:215], v[16:19]
	v_mfma_f32_16x16x32_bf16 v[4:7], v[176:179], v[220:223], v[4:7]
	v_mfma_f32_16x16x32_bf16 v[0:3], v[188:191], v[220:223], v[0:3]
	v_mfma_f32_16x16x32_bf16 v[52:55], v[180:183], v[200:203], v[52:55]
	v_mfma_f32_16x16x32_bf16 v[48:51], v[192:195], v[200:203], v[48:51]
	v_mfma_f32_16x16x32_bf16 v[36:39], v[180:183], v[208:211], v[36:39]
	v_mfma_f32_16x16x32_bf16 v[32:35], v[192:195], v[208:211], v[32:35]
	v_mfma_f32_16x16x32_bf16 v[20:23], v[180:183], v[216:219], v[20:23]
	v_mfma_f32_16x16x32_bf16 v[16:19], v[192:195], v[216:219], v[16:19]
	v_mfma_f32_16x16x32_bf16 v[4:7], v[180:183], v[224:227], v[4:7]
	v_mfma_f32_16x16x32_bf16 v[0:3], v[192:195], v[224:227], v[0:3]
	s_barrier
	s_setprio 0
	s_add_i32 s47, s47, 2
	s_add_u32 s24, s24, 0x100
	s_addc_u32 s25, s25, 0
	s_add_u32 s45, s45, 0x100
	s_addc_u32 s46, s46, 0
	s_cmp_gt_u32 s47, 29

; __device__ __forceinline__ unsigned cvt_pk_bf16(float lo, float hi) { unsigned r; asm volatile("v_cvt_pk_bf16_f32 %0, %1, %2" : "=v"(r) : "v"(lo), "v"(hi)); return r; }
;     __device__ __forceinline__ void operator()(const f32x4 (&acc)[2][2][4][2], const Unit& u, int wr, int wc, int fr, int fq) const {
;         const int row0 = u.pm * BM + wr * 64 + fr, col0 = u.pn * BM + wc * 32 + 8 * fq, b = (u.pm * BM) >> 12;
;         f32x4 cbv[2][2];
; #pragma unroll
;         for (int bj = 0; bj < 2; ++bj)
; #pragma unroll
;             for (int n = 0; n < 2; ++n) cbv[bj][n] = *(const f32x4*)(cb + (size_t)b * 8192 + col0 + bj * HALF + 4 * n);
; #pragma unroll
;         for (int ai = 0; ai < 2; ++ai)
; #pragma unroll
;             for (int m = 0; m < 4; ++m) { const int rl = wr * 64 + fr + ai * HALF + m * 16; bf16_t* rowp = O + (size_t)(u.pm * BM + rl) * ldc + col0;
;                 const float rs = rstd[((u.pm >> 2) & 1) * 256 + rl];
; #pragma unroll
;                 for (int bj = 0; bj < 2; ++bj) { float v[8];
; #pragma unroll
;                     for (int e = 0; e < 8; ++e) { const float x = fmaxf(acc[ai][bj][m][e >> 2][e & 3] * rs + cbv[bj][e >> 2][e & 3], 0.f); v[e] = x * x; }
;                     u32x4 w; w.x = cvt_pk_bf16(v[0], v[1]); w.y = cvt_pk_bf16(v[2], v[3]); w.z = cvt_pk_bf16(v[4], v[5]); w.w = cvt_pk_bf16(v[6], v[7]);
;                     *(u32x4*)(rowp + bj * HALF) = w; } }
.LBB0_997:
	s_ashr_i32 s24, s22, 4
	s_ashr_i32 s25, s24, 31
	s_lshl_b64 s[24:25], s[24:25], 15
	v_lshl_or_b32 v160, s42, 8, v171
	s_add_u32 s24, s36, s24
	s_addc_u32 s25, s37, s25
	v_ashrrev_i32_e32 v161, 31, v160
	s_nop 0
	s_lshl_b32 s15, s22, 8
	s_and_b32 s17, s15, 0x400
	v_add_u32_e32 v176, s17, v172
	ds_read_b32 v177, v176
	v_add_u32_e32 v178, s15, v162
	v_ashrrev_i32_e32 v179, 31, v178
	v_lshlrev_b64 v[178:179], 14, v[178:179]
	v_lshlrev_b64 v[160:161], 1, v[160:161]
	v_lshl_add_u64 v[178:179], s[72:73], 0, v[178:179]
	v_lshl_add_u64 v[178:179], v[178:179], 0, v[160:161]
	v_add_u32_e32 v180, s15, v164
	v_ashrrev_i32_e32 v181, 31, v180
	s_andn2_b64 vcc, exec, s[4:5]
	s_mov_b64 s[4:5], -1
	s_waitcnt lgkmcnt(0)
	v_fma_f32 v124, v124, v177, v240
	v_fma_f32 v125, v125, v177, v241
	v_fma_f32 v126, v126, v177, v242
	v_fma_f32 v127, v127, v177, v243
	v_fma_f32 v120, v120, v177, v244
	v_fma_f32 v121, v121, v177, v245
	v_fma_f32 v122, v122, v177, v246
	v_fma_f32 v123, v123, v177, v247
	v_fma_f32 v118, v118, v177, v250
	v_fma_f32 v112, v112, v177, v252
	v_fma_f32 v113, v113, v177, v253
	v_fma_f32 v114, v114, v177, v254
	v_fma_f32 v115, v115, v177, v255
	v_fma_f32 v116, v116, v177, v248
	v_fma_f32 v117, v117, v177, v249
	v_fma_f32 v119, v119, v177, v251
	v_max_f32_e32 v124, 0, v124
	v_max_f32_e32 v125, 0, v125
	v_max_f32_e32 v126, 0, v126
	v_max_f32_e32 v127, 0, v127
	v_max_f32_e32 v120, 0, v120
	v_max_f32_e32 v121, 0, v121
	v_max_f32_e32 v122, 0, v122
	v_max_f32_e32 v123, 0, v123
	v_max_f32_e32 v118, 0, v118
	v_max_f32_e32 v112, 0, v112
	v_max_f32_e32 v113, 0, v113
	v_max_f32_e32 v114, 0, v114
	v_max_f32_e32 v115, 0, v115
	v_max_f32_e32 v116, 0, v116
	v_max_f32_e32 v117, 0, v117
	v_max_f32_e32 v119, 0, v119
	v_mul_f32_e32 v124, v124, v124
	v_mul_f32_e32 v125, v125, v125
	v_mul_f32_e32 v126, v126, v126
	v_mul_f32_e32 v127, v127, v127
	v_mul_f32_e32 v120, v120, v120
	v_mul_f32_e32 v121, v121, v121
	v_mul_f32_e32 v122, v122, v122
	v_mul_f32_e32 v123, v123, v123
	v_mul_f32_e32 v118, v118, v118
	v_mul_f32_e32 v177, v112, v112
	v_mul_f32_e32 v182, v113, v113
	v_mul_f32_e32 v183, v114, v114
	v_mul_f32_e32 v184, v115, v115
	v_cvt_pk_bf16_f32 v112, v124, v125
	v_cvt_pk_bf16_f32 v113, v126, v127
	v_cvt_pk_bf16_f32 v114, v120, v121
	v_cvt_pk_bf16_f32 v115, v122, v123
	v_mul_f32_e32 v116, v116, v116
	v_mul_f32_e32 v117, v117, v117
	v_mul_f32_e32 v119, v119, v119
	global_store_dwordx4 v[178:179], v[112:115], off
	s_nop 1
	v_cvt_pk_bf16_f32 v112, v116, v117
	v_cvt_pk_bf16_f32 v113, v118, v119
	v_cvt_pk_bf16_f32 v114, v177, v182
	v_cvt_pk_bf16_f32 v115, v183, v184
	ds_read_b32 v118, v176 offset:64
	global_store_dwordx4 v[178:179], v[112:115], off offset:256
	v_lshlrev_b64 v[116:117], 14, v[180:181]
	v_lshl_add_u64 v[116:117], s[72:73], 0, v[116:117]
	v_lshl_add_u64 v[116:117], v[116:117], 0, v[160:161]
	s_waitcnt lgkmcnt(0)
	v_fma_f32 v104, v104, v118, v244
	v_max_f32_e32 v104, 0, v104
	v_mul_f32_e32 v112, v104, v104
	v_fma_f32 v104, v105, v118, v245
	v_max_f32_e32 v104, 0, v104
	v_mul_f32_e32 v113, v104, v104
	v_fma_f32 v104, v106, v118, v246
	v_max_f32_e32 v104, 0, v104
	v_fma_f32 v108, v108, v118, v240
	v_fma_f32 v109, v109, v118, v241
	v_mul_f32_e32 v114, v104, v104
	v_fma_f32 v104, v107, v118, v247
	v_fma_f32 v110, v110, v118, v242
	v_fma_f32 v111, v111, v118, v243
	v_max_f32_e32 v108, 0, v108
	v_max_f32_e32 v109, 0, v109
	v_max_f32_e32 v104, 0, v104
	v_fma_f32 v96, v96, v118, v252
	v_max_f32_e32 v110, 0, v110
	v_max_f32_e32 v111, 0, v111
	v_mul_f32_e32 v108, v108, v108
	v_mul_f32_e32 v109, v109, v109
	v_mul_f32_e32 v107, v104, v104
	v_cvt_pk_bf16_f32 v104, v108, v109
	v_max_f32_e32 v96, 0, v96
	v_mul_f32_e32 v110, v110, v110
	v_mul_f32_e32 v111, v111, v111
	v_cvt_pk_bf16_f32 v105, v110, v111
	v_cvt_pk_bf16_f32 v106, v112, v113
	v_cvt_pk_bf16_f32 v107, v114, v107
	global_store_dwordx4 v[116:117], v[104:107], off
	v_fma_f32 v100, v100, v118, v248
	v_fma_f32 v101, v101, v118, v249
	v_mul_f32_e32 v104, v96, v96
	v_fma_f32 v96, v97, v118, v253
	v_max_f32_e32 v96, 0, v96
	v_mul_f32_e32 v105, v96, v96
	v_fma_f32 v96, v98, v118, v254
	v_max_f32_e32 v96, 0, v96
	v_fma_f32 v102, v102, v118, v250
	v_fma_f32 v103, v103, v118, v251
	v_mul_f32_e32 v106, v96, v96
	v_fma_f32 v96, v99, v118, v255
	v_max_f32_e32 v100, 0, v100
	v_max_f32_e32 v101, 0, v101
	v_max_f32_e32 v102, 0, v102
	v_max_f32_e32 v103, 0, v103
	v_max_f32_e32 v96, 0, v96
	v_mul_f32_e32 v100, v100, v100
	v_mul_f32_e32 v101, v101, v101
	v_mul_f32_e32 v102, v102, v102
	v_mul_f32_e32 v103, v103, v103
	v_mul_f32_e32 v99, v96, v96
	v_cvt_pk_bf16_f32 v96, v100, v101
	v_cvt_pk_bf16_f32 v97, v102, v103
	v_cvt_pk_bf16_f32 v98, v104, v105
	v_cvt_pk_bf16_f32 v99, v106, v99
	global_store_dwordx4 v[116:117], v[96:99], off offset:256
	ds_read_b32 v98, v176 offset:128
	s_waitcnt lgkmcnt(0)
; __device__ __forceinline__ unsigned cvt_pk_bf16(float lo, float hi) { unsigned r; asm volatile("v_cvt_pk_bf16_f32 %0, %1, %2" : "=v"(r) : "v"(lo), "v"(hi)); return r; }
;     __device__ __forceinline__ void operator()(const f32x4 (&acc)[2][2][4][2], const Unit& u, int wr, int wc, int fr, int fq) const {
;     ...
;         for (int ai = 0; ai < 2; ++ai)
; #pragma unroll
;             for (int m = 0; m < 4; ++m) { const int rl = wr * 64 + fr + ai * HALF + m * 16; bf16_t* rowp = O + (size_t)(u.pm * BM + rl) * ldc + col0;
;                 const float rs = rstd[((u.pm >> 2) & 1) * 256 + rl];
; #pragma unroll
;                 for (int bj = 0; bj < 2; ++bj) { float v[8];
; #pragma unroll
;                     for (int e = 0; e < 8; ++e) { const float x = fmaxf(acc[ai][bj][m][e >> 2][e & 3] * rs + cbv[bj][e >> 2][e & 3], 0.f); v[e] = x * x; }
;                     u32x4 w; w.x = cvt_pk_bf16(v[0], v[1]); w.y = cvt_pk_bf16(v[2], v[3]); w.z = cvt_pk_bf16(v[4], v[5]); w.w = cvt_pk_bf16(v[6], v[7]);
;                     *(u32x4*)(rowp + bj * HALF) = w; } }
	v_fma_f32 v88, v88, v98, v244
	v_max_f32_e32 v88, 0, v88
	v_mul_f32_e32 v99, v88, v88
	v_fma_f32 v88, v89, v98, v245
	v_max_f32_e32 v88, 0, v88
	v_add_u32_e32 v96, s15, v165
	v_mul_f32_e32 v100, v88, v88
	v_fma_f32 v88, v90, v98, v246
	v_ashrrev_i32_e32 v97, 31, v96
	v_max_f32_e32 v88, 0, v88
	v_lshlrev_b64 v[96:97], 14, v[96:97]
	v_fma_f32 v92, v92, v98, v240
	v_fma_f32 v93, v93, v98, v241
	v_mul_f32_e32 v101, v88, v88
	v_fma_f32 v88, v91, v98, v247
	v_lshl_add_u64 v[96:97], s[72:73], 0, v[96:97]
	v_max_f32_e32 v92, 0, v92
	v_max_f32_e32 v93, 0, v93
	v_fma_f32 v94, v94, v98, v242
	v_fma_f32 v95, v95, v98, v243
	v_max_f32_e32 v88, 0, v88
	v_fma_f32 v80, v80, v98, v252
	v_lshl_add_u64 v[96:97], v[96:97], 0, v[160:161]
	v_mul_f32_e32 v92, v92, v92
	v_mul_f32_e32 v93, v93, v93
	v_max_f32_e32 v94, 0, v94
	v_max_f32_e32 v95, 0, v95
	v_mul_f32_e32 v91, v88, v88
	v_cvt_pk_bf16_f32 v88, v92, v93
	v_max_f32_e32 v80, 0, v80
	v_mul_f32_e32 v94, v94, v94
	v_mul_f32_e32 v95, v95, v95
	v_cvt_pk_bf16_f32 v89, v94, v95
	v_cvt_pk_bf16_f32 v90, v99, v100
	v_cvt_pk_bf16_f32 v91, v101, v91
	global_store_dwordx4 v[96:97], v[88:91], off
	v_fma_f32 v84, v84, v98, v248
	v_fma_f32 v85, v85, v98, v249
	v_mul_f32_e32 v88, v80, v80
	v_fma_f32 v80, v81, v98, v253
	v_max_f32_e32 v80, 0, v80
	v_mul_f32_e32 v89, v80, v80
	v_fma_f32 v80, v82, v98, v254
	v_max_f32_e32 v80, 0, v80
	v_fma_f32 v86, v86, v98, v250
	v_fma_f32 v87, v87, v98, v251
	v_mul_f32_e32 v90, v80, v80
	v_fma_f32 v80, v83, v98, v255
	v_max_f32_e32 v84, 0, v84
	v_max_f32_e32 v85, 0, v85
	v_max_f32_e32 v86, 0, v86
	v_max_f32_e32 v87, 0, v87
	v_max_f32_e32 v80, 0, v80
	v_mul_f32_e32 v84, v84, v84
	v_mul_f32_e32 v85, v85, v85
	v_mul_f32_e32 v86, v86, v86
	v_mul_f32_e32 v87, v87, v87
	v_mul_f32_e32 v83, v80, v80
	v_cvt_pk_bf16_f32 v80, v84, v85
	v_cvt_pk_bf16_f32 v81, v86, v87
	v_cvt_pk_bf16_f32 v82, v88, v89
	v_cvt_pk_bf16_f32 v83, v90, v83
	global_store_dwordx4 v[96:97], v[80:83], off offset:256
	ds_read_b32 v82, v176 offset:192
	s_waitcnt lgkmcnt(0)
	v_fma_f32 v72, v72, v82, v244
	v_max_f32_e32 v72, 0, v72
	v_mul_f32_e32 v83, v72, v72
	v_fma_f32 v72, v73, v82, v245
	v_max_f32_e32 v72, 0, v72
	v_add_u32_e32 v80, s15, v166
	v_mul_f32_e32 v84, v72, v72
	v_fma_f32 v72, v74, v82, v246
	v_ashrrev_i32_e32 v81, 31, v80
	v_max_f32_e32 v72, 0, v72
	v_lshlrev_b64 v[80:81], 14, v[80:81]
	v_fma_f32 v76, v76, v82, v240
	v_fma_f32 v77, v77, v82, v241
	v_mul_f32_e32 v85, v72, v72
	v_fma_f32 v72, v75, v82, v247
	v_lshl_add_u64 v[80:81], s[72:73], 0, v[80:81]
	v_max_f32_e32 v76, 0, v76
	v_max_f32_e32 v77, 0, v77
	v_fma_f32 v78, v78, v82, v242
	v_fma_f32 v79, v79, v82, v243
	v_max_f32_e32 v72, 0, v72
	v_fma_f32 v64, v64, v82, v252
	v_lshl_add_u64 v[80:81], v[80:81], 0, v[160:161]
	v_mul_f32_e32 v76, v76, v76
	v_mul_f32_e32 v77, v77, v77
	v_max_f32_e32 v78, 0, v78
	v_max_f32_e32 v79, 0, v79
	v_mul_f32_e32 v75, v72, v72
	v_cvt_pk_bf16_f32 v72, v76, v77
	v_max_f32_e32 v64, 0, v64
	v_mul_f32_e32 v78, v78, v78
	v_mul_f32_e32 v79, v79, v79
	v_cvt_pk_bf16_f32 v73, v78, v79
	v_cvt_pk_bf16_f32 v74, v83, v84
	v_cvt_pk_bf16_f32 v75, v85, v75
	global_store_dwordx4 v[80:81], v[72:75], off
	v_fma_f32 v68, v68, v82, v248
	v_fma_f32 v69, v69, v82, v249
	v_mul_f32_e32 v72, v64, v64
	v_fma_f32 v64, v65, v82, v253
	v_max_f32_e32 v64, 0, v64
	v_mul_f32_e32 v73, v64, v64
	v_fma_f32 v64, v66, v82, v254
	v_max_f32_e32 v64, 0, v64
	v_fma_f32 v70, v70, v82, v250
	v_fma_f32 v71, v71, v82, v251
	v_mul_f32_e32 v74, v64, v64
	v_fma_f32 v64, v67, v82, v255
	v_max_f32_e32 v68, 0, v68
	v_max_f32_e32 v69, 0, v69
	v_max_f32_e32 v70, 0, v70
	v_max_f32_e32 v71, 0, v71
	v_max_f32_e32 v64, 0, v64
	v_mul_f32_e32 v68, v68, v68
	v_mul_f32_e32 v69, v69, v69
	v_mul_f32_e32 v70, v70, v70
	v_mul_f32_e32 v71, v71, v71
	v_mul_f32_e32 v67, v64, v64
	v_cvt_pk_bf16_f32 v64, v68, v69
	v_cvt_pk_bf16_f32 v65, v70, v71
	v_cvt_pk_bf16_f32 v66, v72, v73
	v_cvt_pk_bf16_f32 v67, v74, v67
	global_store_dwordx4 v[80:81], v[64:67], off offset:256
	ds_read_b32 v66, v176 offset:512
	s_waitcnt lgkmcnt(0)
	v_fma_f32 v56, v56, v66, v244
	v_max_f32_e32 v56, 0, v56
	v_mul_f32_e32 v67, v56, v56
	v_fma_f32 v56, v57, v66, v245
	v_max_f32_e32 v56, 0, v56
	v_add_u32_e32 v64, s15, v167
	v_mul_f32_e32 v68, v56, v56
	v_fma_f32 v56, v58, v66, v246
	v_ashrrev_i32_e32 v65, 31, v64
	v_max_f32_e32 v56, 0, v56
	v_lshlrev_b64 v[64:65], 14, v[64:65]
	v_fma_f32 v60, v60, v66, v240
	v_fma_f32 v61, v61, v66, v241
	v_mul_f32_e32 v69, v56, v56
	v_fma_f32 v56, v59, v66, v247
	v_lshl_add_u64 v[64:65], s[72:73], 0, v[64:65]
	v_max_f32_e32 v60, 0, v60
	v_max_f32_e32 v61, 0, v61
	v_fma_f32 v62, v62, v66, v242
	v_fma_f32 v63, v63, v66, v243
	v_max_f32_e32 v56, 0, v56
	v_fma_f32 v48, v48, v66, v252
	v_lshl_add_u64 v[64:65], v[64:65], 0, v[160:161]
	v_mul_f32_e32 v60, v60, v60
	v_mul_f32_e32 v61, v61, v61
	v_max_f32_e32 v62, 0, v62
	v_max_f32_e32 v63, 0, v63
	v_mul_f32_e32 v59, v56, v56
	v_cvt_pk_bf16_f32 v56, v60, v61
	v_max_f32_e32 v48, 0, v48
	v_mul_f32_e32 v62, v62, v62
	v_mul_f32_e32 v63, v63, v63
	v_cvt_pk_bf16_f32 v57, v62, v63
	v_cvt_pk_bf16_f32 v58, v67, v68
	v_cvt_pk_bf16_f32 v59, v69, v59
	global_store_dwordx4 v[64:65], v[56:59], off
	v_fma_f32 v52, v52, v66, v248
	v_fma_f32 v53, v53, v66, v249
	v_mul_f32_e32 v56, v48, v48
	v_fma_f32 v48, v49, v66, v253
	v_max_f32_e32 v48, 0, v48
	v_mul_f32_e32 v57, v48, v48
	v_fma_f32 v48, v50, v66, v254
	v_max_f32_e32 v48, 0, v48
	v_fma_f32 v54, v54, v66, v250
	v_fma_f32 v55, v55, v66, v251
	v_mul_f32_e32 v58, v48, v48
	v_fma_f32 v48, v51, v66, v255
	v_max_f32_e32 v52, 0, v52
	v_max_f32_e32 v53, 0, v53
	v_max_f32_e32 v54, 0, v54
	v_max_f32_e32 v55, 0, v55
	v_max_f32_e32 v48, 0, v48
	v_mul_f32_e32 v52, v52, v52
	v_mul_f32_e32 v53, v53, v53
	v_mul_f32_e32 v54, v54, v54
	v_mul_f32_e32 v55, v55, v55
	v_mul_f32_e32 v51, v48, v48
	v_cvt_pk_bf16_f32 v48, v52, v53
	v_cvt_pk_bf16_f32 v49, v54, v55
	v_cvt_pk_bf16_f32 v50, v56, v57
	v_cvt_pk_bf16_f32 v51, v58, v51
	global_store_dwordx4 v[64:65], v[48:51], off offset:256
	ds_read_b32 v50, v176 offset:576
	s_waitcnt lgkmcnt(0)
; __device__ __forceinline__ unsigned cvt_pk_bf16(float lo, float hi) { unsigned r; asm volatile("v_cvt_pk_bf16_f32 %0, %1, %2" : "=v"(r) : "v"(lo), "v"(hi)); return r; }
; #define PG8_BAR __builtin_amdgcn_s_barrier()
;     __device__ __forceinline__ void operator()(const f32x4 (&acc)[2][2][4][2], const Unit& u, int wr, int wc, int fr, int fq) const {
;     ...
;         for (int ai = 0; ai < 2; ++ai)
; #pragma unroll
;             for (int m = 0; m < 4; ++m) { const int rl = wr * 64 + fr + ai * HALF + m * 16; bf16_t* rowp = O + (size_t)(u.pm * BM + rl) * ldc + col0;
;                 const float rs = rstd[((u.pm >> 2) & 1) * 256 + rl];
; #pragma unroll
;                 for (int bj = 0; bj < 2; ++bj) { float v[8];
; #pragma unroll
;                     for (int e = 0; e < 8; ++e) { const float x = fmaxf(acc[ai][bj][m][e >> 2][e & 3] * rs + cbv[bj][e >> 2][e & 3], 0.f); v[e] = x * x; }
;                     u32x4 w; w.x = cvt_pk_bf16(v[0], v[1]); w.y = cvt_pk_bf16(v[2], v[3]); w.z = cvt_pk_bf16(v[4], v[5]); w.w = cvt_pk_bf16(v[6], v[7]);
;                     *(u32x4*)(rowp + bj * HALF) = w; } }
; template <class Epi, class Sched, bool ALIGN_EPI = false, bool SP2 = false>
; __device__ __forceinline__ void gemm_phase(PG8_LAS unsigned char* lds, const Gemm g, const Sched& S, const Epi& E) {
;     ...
;         if (!has_next) break;
; #pragma unroll
;         for (int a = 0; a < 2; ++a)
; #pragma unroll
;             for (int b = 0; b < 2; ++b)
; #pragma unroll
;                 for (int m = 0; m < 4; ++m)
; #pragma unroll
;                     for (int n = 0; n < 2; ++n) acc[a][b][m][n] = (f32x4){0.f, 0.f, 0.f, 0.f};
;         cur = nxt; cA = nA; cB = nB; ++ui;
;         if constexpr (ALIGN_EPI) { if (wr == 1) PG8_BAR; }
	v_fma_f32 v40, v40, v50, v244
	v_max_f32_e32 v40, 0, v40
	v_mul_f32_e32 v51, v40, v40
	v_fma_f32 v40, v41, v50, v245
	v_max_f32_e32 v40, 0, v40
	v_add_u32_e32 v48, s15, v168
	v_mul_f32_e32 v52, v40, v40
	v_fma_f32 v40, v42, v50, v246
	v_ashrrev_i32_e32 v49, 31, v48
	v_max_f32_e32 v40, 0, v40
	v_lshlrev_b64 v[48:49], 14, v[48:49]
	v_fma_f32 v44, v44, v50, v240
	v_fma_f32 v45, v45, v50, v241
	v_mul_f32_e32 v53, v40, v40
	v_fma_f32 v40, v43, v50, v247
	v_lshl_add_u64 v[48:49], s[72:73], 0, v[48:49]
	v_max_f32_e32 v44, 0, v44
	v_max_f32_e32 v45, 0, v45
	v_fma_f32 v46, v46, v50, v242
	v_fma_f32 v47, v47, v50, v243
	v_max_f32_e32 v40, 0, v40
	v_fma_f32 v32, v32, v50, v252
	v_lshl_add_u64 v[48:49], v[48:49], 0, v[160:161]
	v_mul_f32_e32 v44, v44, v44
	v_mul_f32_e32 v45, v45, v45
	v_max_f32_e32 v46, 0, v46
	v_max_f32_e32 v47, 0, v47
	v_mul_f32_e32 v43, v40, v40
	v_cvt_pk_bf16_f32 v40, v44, v45
	v_max_f32_e32 v32, 0, v32
	v_mul_f32_e32 v46, v46, v46
	v_mul_f32_e32 v47, v47, v47
	v_cvt_pk_bf16_f32 v41, v46, v47
	v_cvt_pk_bf16_f32 v42, v51, v52
	v_cvt_pk_bf16_f32 v43, v53, v43
	global_store_dwordx4 v[48:49], v[40:43], off
	v_fma_f32 v36, v36, v50, v248
	v_fma_f32 v37, v37, v50, v249
	v_mul_f32_e32 v40, v32, v32
	v_fma_f32 v32, v33, v50, v253
	v_max_f32_e32 v32, 0, v32
	v_mul_f32_e32 v41, v32, v32
	v_fma_f32 v32, v34, v50, v254
	v_max_f32_e32 v32, 0, v32
	v_fma_f32 v38, v38, v50, v250
	v_fma_f32 v39, v39, v50, v251
	v_mul_f32_e32 v42, v32, v32
	v_fma_f32 v32, v35, v50, v255
	v_max_f32_e32 v36, 0, v36
	v_max_f32_e32 v37, 0, v37
	v_max_f32_e32 v38, 0, v38
	v_max_f32_e32 v39, 0, v39
	v_max_f32_e32 v32, 0, v32
	v_mul_f32_e32 v36, v36, v36
	v_mul_f32_e32 v37, v37, v37
	v_mul_f32_e32 v38, v38, v38
	v_mul_f32_e32 v39, v39, v39
	v_mul_f32_e32 v35, v32, v32
	v_cvt_pk_bf16_f32 v32, v36, v37
	v_cvt_pk_bf16_f32 v33, v38, v39
	v_cvt_pk_bf16_f32 v34, v40, v41
	v_cvt_pk_bf16_f32 v35, v42, v35
	global_store_dwordx4 v[48:49], v[32:35], off offset:256
	ds_read_b32 v34, v176 offset:640
	s_waitcnt lgkmcnt(0)
	v_fma_f32 v24, v24, v34, v244
	v_max_f32_e32 v24, 0, v24
	v_mul_f32_e32 v35, v24, v24
	v_fma_f32 v24, v25, v34, v245
	v_max_f32_e32 v24, 0, v24
	v_add_u32_e32 v32, s15, v169
	v_mul_f32_e32 v36, v24, v24
	v_fma_f32 v24, v26, v34, v246
	v_ashrrev_i32_e32 v33, 31, v32
	v_max_f32_e32 v24, 0, v24
	v_lshlrev_b64 v[32:33], 14, v[32:33]
	v_fma_f32 v28, v28, v34, v240
	v_fma_f32 v29, v29, v34, v241
	v_mul_f32_e32 v37, v24, v24
	v_fma_f32 v24, v27, v34, v247
	v_lshl_add_u64 v[32:33], s[72:73], 0, v[32:33]
	v_max_f32_e32 v28, 0, v28
	v_max_f32_e32 v29, 0, v29
	v_fma_f32 v30, v30, v34, v242
	v_fma_f32 v31, v31, v34, v243
	v_max_f32_e32 v24, 0, v24
	v_fma_f32 v16, v16, v34, v252
	v_lshl_add_u64 v[32:33], v[32:33], 0, v[160:161]
	v_mul_f32_e32 v28, v28, v28
	v_mul_f32_e32 v29, v29, v29
	v_max_f32_e32 v30, 0, v30
	v_max_f32_e32 v31, 0, v31
	v_mul_f32_e32 v27, v24, v24
	v_cvt_pk_bf16_f32 v24, v28, v29
	v_max_f32_e32 v16, 0, v16
	v_mul_f32_e32 v30, v30, v30
	v_mul_f32_e32 v31, v31, v31
	v_cvt_pk_bf16_f32 v25, v30, v31
	v_cvt_pk_bf16_f32 v26, v35, v36
	v_cvt_pk_bf16_f32 v27, v37, v27
	global_store_dwordx4 v[32:33], v[24:27], off
	v_fma_f32 v20, v20, v34, v248
	v_fma_f32 v21, v21, v34, v249
	v_mul_f32_e32 v24, v16, v16
	v_fma_f32 v16, v17, v34, v253
	v_max_f32_e32 v16, 0, v16
	v_mul_f32_e32 v25, v16, v16
	v_fma_f32 v16, v18, v34, v254
	v_max_f32_e32 v16, 0, v16
	v_fma_f32 v22, v22, v34, v250
	v_fma_f32 v23, v23, v34, v251
	v_mul_f32_e32 v26, v16, v16
	v_fma_f32 v16, v19, v34, v255
	v_max_f32_e32 v20, 0, v20
	v_max_f32_e32 v21, 0, v21
	v_max_f32_e32 v22, 0, v22
	v_max_f32_e32 v23, 0, v23
	v_max_f32_e32 v16, 0, v16
	v_mul_f32_e32 v20, v20, v20
	v_mul_f32_e32 v21, v21, v21
	v_mul_f32_e32 v22, v22, v22
	v_mul_f32_e32 v23, v23, v23
	v_mul_f32_e32 v19, v16, v16
	v_cvt_pk_bf16_f32 v16, v20, v21
	v_cvt_pk_bf16_f32 v17, v22, v23
	v_cvt_pk_bf16_f32 v18, v24, v25
	v_cvt_pk_bf16_f32 v19, v26, v19
	global_store_dwordx4 v[32:33], v[16:19], off offset:256
	ds_read_b32 v18, v176 offset:704
	s_waitcnt lgkmcnt(0)
	v_fma_f32 v8, v8, v18, v244
	v_max_f32_e32 v8, 0, v8
	v_mul_f32_e32 v19, v8, v8
	v_fma_f32 v8, v9, v18, v245
	v_add_u32_e32 v16, s15, v170
	v_max_f32_e32 v8, 0, v8
	v_ashrrev_i32_e32 v17, 31, v16
	v_mul_f32_e32 v20, v8, v8
	v_fma_f32 v8, v10, v18, v246
	v_lshlrev_b64 v[16:17], 14, v[16:17]
	v_fma_f32 v12, v12, v18, v240
	v_fma_f32 v13, v13, v18, v241
	v_max_f32_e32 v8, 0, v8
	v_fmac_f32_e32 v247, v11, v18
	v_lshl_add_u64 v[16:17], s[72:73], 0, v[16:17]
	v_max_f32_e32 v12, 0, v12
	v_max_f32_e32 v13, 0, v13
	v_fma_f32 v14, v14, v18, v242
	v_fmac_f32_e32 v243, v15, v18
	v_mul_f32_e32 v21, v8, v8
	v_max_f32_e32 v8, 0, v247
	v_fma_f32 v0, v0, v18, v252
	v_lshl_add_u64 v[16:17], v[16:17], 0, v[160:161]
	v_mul_f32_e32 v12, v12, v12
	v_mul_f32_e32 v13, v13, v13
	v_max_f32_e32 v14, 0, v14
	v_max_f32_e32 v15, 0, v243
	v_mul_f32_e32 v11, v8, v8
	v_cvt_pk_bf16_f32 v8, v12, v13
	v_max_f32_e32 v0, 0, v0
	v_mul_f32_e32 v14, v14, v14
	v_mul_f32_e32 v15, v15, v15
	v_cvt_pk_bf16_f32 v9, v14, v15
	v_cvt_pk_bf16_f32 v10, v19, v20
	v_cvt_pk_bf16_f32 v11, v21, v11
	global_store_dwordx4 v[16:17], v[8:11], off
	v_fmac_f32_e32 v255, v3, v18
	v_fma_f32 v4, v4, v18, v248
	v_mul_f32_e32 v8, v0, v0
	v_fma_f32 v0, v1, v18, v253
	v_max_f32_e32 v0, 0, v0
	v_mul_f32_e32 v9, v0, v0
	v_fma_f32 v0, v2, v18, v254
	v_max_f32_e32 v0, 0, v0
	v_fma_f32 v5, v5, v18, v249
	v_fma_f32 v6, v6, v18, v250
	v_fmac_f32_e32 v251, v7, v18
	v_mul_f32_e32 v10, v0, v0
	v_max_f32_e32 v0, 0, v255
	v_max_f32_e32 v4, 0, v4
	v_max_f32_e32 v5, 0, v5
	v_max_f32_e32 v6, 0, v6
	v_max_f32_e32 v7, 0, v251
	v_mul_f32_e32 v3, v0, v0
	v_mul_f32_e32 v4, v4, v4
	v_mul_f32_e32 v5, v5, v5
	v_mul_f32_e32 v6, v6, v6
	v_mul_f32_e32 v7, v7, v7
	v_cvt_pk_bf16_f32 v0, v4, v5
	v_cvt_pk_bf16_f32 v1, v6, v7
	v_cvt_pk_bf16_f32 v2, v8, v9
	v_cvt_pk_bf16_f32 v3, v10, v3
	global_store_dwordx4 v[16:17], v[0:3], off offset:256
	s_cbranch_vccnz .LBB0_986
	s_andn2_b64 vcc, exec, s[6:7]
	s_cbranch_vccnz .LBB0_985
	s_barrier
	s_branch .LBB0_985

; __global__ void __launch_bounds__(NTHR, 2) fwd_megakernel(Args a) {
	.amdhsa_kernel _Z14fwd_megakernel4Args
		.amdhsa_group_segment_fixed_size 0
		.amdhsa_private_segment_fixed_size 0
		.amdhsa_kernarg_size 408
		.amdhsa_user_sgpr_count 2
		.amdhsa_user_sgpr_dispatch_ptr 0
		.amdhsa_user_sgpr_queue_ptr 0
		.amdhsa_user_sgpr_kernarg_segment_ptr 1
		.amdhsa_user_sgpr_dispatch_id 0
		.amdhsa_user_sgpr_kernarg_preload_length 0
		.amdhsa_user_sgpr_kernarg_preload_offset 0
		.amdhsa_user_sgpr_private_segment_size 0
		.amdhsa_uses_dynamic_stack 0
		.amdhsa_enable_private_segment 0
		.amdhsa_system_sgpr_workgroup_id_x 1
		.amdhsa_system_sgpr_workgroup_id_y 0
		.amdhsa_system_sgpr_workgroup_id_z 0
		.amdhsa_system_sgpr_workgroup_info 0
		.amdhsa_system_vgpr_workitem_id 2
		.amdhsa_next_free_vgpr 256
		.amdhsa_next_free_sgpr 102
		.amdhsa_accum_offset 256
		.amdhsa_reserve_vcc 1
		.amdhsa_float_round_mode_32 0
		.amdhsa_float_round_mode_16_64 0
		.amdhsa_float_denorm_mode_32 3
		.amdhsa_float_denorm_mode_16_64 3
		.amdhsa_dx10_clamp 1
		.amdhsa_ieee_mode 1
		.amdhsa_fp16_overflow 0
		.amdhsa_tg_split 0
		.amdhsa_exception_fp_ieee_invalid_op 0
		.amdhsa_exception_fp_denorm_src 0
		.amdhsa_exception_fp_ieee_div_zero 0
		.amdhsa_exception_fp_ieee_overflow 0
		.amdhsa_exception_fp_ieee_underflow 0
		.amdhsa_exception_fp_ieee_inexact 0
		.amdhsa_exception_int_div_zero 0
	.end_amdhsa_kernel

; __global__ void __launch_bounds__(NTHR, 2) fwd_megakernel(Args a) {
amdhsa.kernels:
  - .agpr_count:     0
    .args:
      - .offset:         0
        .size:           152
        .value_kind:     by_value
      - .offset:         152
        .size:           4
        .value_kind:     hidden_block_count_x
      - .offset:         156
        .size:           4
        .value_kind:     hidden_block_count_y
      - .offset:         160
        .size:           4
        .value_kind:     hidden_block_count_z
      - .offset:         164
        .size:           2
        .value_kind:     hidden_group_size_x
      - .offset:         166
        .size:           2
        .value_kind:     hidden_group_size_y
      - .offset:         168
        .size:           2
        .value_kind:     hidden_group_size_z
      - .offset:         170
        .size:           2
        .value_kind:     hidden_remainder_x
      - .offset:         172
        .size:           2
        .value_kind:     hidden_remainder_y
      - .offset:         174
        .size:           2
        .value_kind:     hidden_remainder_z
      - .offset:         192
        .size:           8
        .value_kind:     hidden_global_offset_x
      - .offset:         200
        .size:           8
        .value_kind:     hidden_global_offset_y
      - .offset:         208
        .size:           8
        .value_kind:     hidden_global_offset_z
      - .offset:         216
        .size:           2
        .value_kind:     hidden_grid_dims
      - .offset:         240
        .size:           8
        .value_kind:     hidden_multigrid_sync_arg
      - .offset:         272
        .size:           4
        .value_kind:     hidden_dynamic_lds_size
    .group_segment_fixed_size: 0
    .kernarg_segment_align: 8
    .kernarg_segment_size: 408
    .language:       OpenCL C
    .language_version:
      - 2
      - 0
    .max_flat_workgroup_size: 512
    .name:           _Z14fwd_megakernel4Args
    .private_segment_fixed_size: 0
    .sgpr_count:     108
    .sgpr_spill_count: 83
    .symbol:         _Z14fwd_megakernel4Args.kd
    .uniform_work_group_size: 1
    .uses_dynamic_stack: false
    .vgpr_count:     256
    .vgpr_spill_count: 0
    .wavefront_size: 64
